# convert loop: counted vmcnt(4) at back-edge so previous item's stores stay in flight
# baseline (speedup 1.0000x reference)
;     const int k0 = 64 * kb;
;     float wv[32];
; #pragma unroll
;     for (int i = 0; i < 32; ++i) { const int kk = 2 * i + (lane >> 5); wv[i] = W[(size_t)(k0 + kk) * N + n0 + (lane & 31)]; }
; #pragma unroll
;     for (int i = 0; i < 32; ++i) { const int kk = 2 * i + (lane >> 5); scr[kk * 33 + (lane & 31)] = wv[i]; }
; __device__ __forceinline__ void phase_convert_weights(const Args& a, int l, LAS unsigned char* lds) {
;     ...
;     for (int it = gw; it < NITEMS; it += NGW) {
;         int r = it;
;         if (r < 2 * I_UP) {
;             const int which = r / I_UP; r -= which * I_UP;
;             const float* W = a.in[which ? I_UP2 : I_UP1] + (size_t)l * DM * NUP; bf16_t* WT = (bf16_t*)(ws + (which ? W_UP2 : W_UP1));
;             const int kb = r / 176, n0 = (r % 176) * 32, half = n0 / DFF, j = n0 % DFF;
;             transpose_item(W, DM, NUP, WT, kb, n0, 256 * (j / 128) + 128 * half + (j % 128), scr, lane); continue; }
.Lcv_common1:
	s_add_u32 s0, s48, s43
	s_addc_u32 s1, s49, 0
	s_load_dwordx2 s[30:31], s[0:1], 0x0
	s_lshl_b32 s26, s27, 6
	s_mul_i32 s25, s26, s36
	s_lshl_b32 s43, s28, 2
	s_add_i32 s25, s25, s43
	s_add_i32 s51, s51, s25
	s_mul_i32 s25, s29, s37
	s_lshl_b32 s26, s26, 1
	s_add_i32 s25, s25, s26
	s_add_i32 s52, s52, s25
	s_add_u32 s34, s22, s52
	s_addc_u32 s35, s23, 0
	s_waitcnt lgkmcnt(0)
	s_add_u32 s30, s30, s51
	s_addc_u32 s31, s31, 0
	v_mad_u32_u24 v5, v1, s36, v2
	s_lshl_b32 s0, s36, 3
	global_load_dwordx4 v[8:11], v5, s[30:31]
	v_add_u32_e32 v5, s0, v5
	global_load_dwordx4 v[12:15], v5, s[30:31]
	v_add_u32_e32 v5, s0, v5
	global_load_dwordx4 v[16:19], v5, s[30:31]
	v_add_u32_e32 v5, s0, v5
	global_load_dwordx4 v[20:23], v5, s[30:31]
	v_add_u32_e32 v5, s0, v5
	global_load_dwordx4 v[24:27], v5, s[30:31]
	v_add_u32_e32 v5, s0, v5
	global_load_dwordx4 v[28:31], v5, s[30:31]
	v_add_u32_e32 v5, s0, v5
	global_load_dwordx4 v[32:35], v5, s[30:31]
	v_add_u32_e32 v5, s0, v5
	global_load_dwordx4 v[36:39], v5, s[30:31]
	s_waitcnt vmcnt(0)
.Lcv_loop:
	s_mov_b64 s[56:57], s[34:35]
	s_mov_b32 s53, s37
	s_mov_b32 s50, s42
	ds_write_b32 v3, v8
	ds_write_b32 v3, v9 offset:4
	ds_write_b32 v3, v10 offset:8
	ds_write_b32 v3, v11 offset:12
	ds_write_b32 v3, v12 offset:1056
	ds_write_b32 v3, v13 offset:1060
	ds_write_b32 v3, v14 offset:1064
	ds_write_b32 v3, v15 offset:1068
	ds_write_b32 v3, v16 offset:2112
	ds_write_b32 v3, v17 offset:2116
	ds_write_b32 v3, v18 offset:2120
	ds_write_b32 v3, v19 offset:2124
	ds_write_b32 v3, v20 offset:3168
	ds_write_b32 v3, v21 offset:3172
	ds_write_b32 v3, v22 offset:3176
	ds_write_b32 v3, v23 offset:3180
	ds_write_b32 v3, v24 offset:4224
	ds_write_b32 v3, v25 offset:4228
	ds_write_b32 v3, v26 offset:4232
	ds_write_b32 v3, v27 offset:4236
	ds_write_b32 v3, v28 offset:5280
	ds_write_b32 v3, v29 offset:5284
	ds_write_b32 v3, v30 offset:5288
	ds_write_b32 v3, v31 offset:5292
	ds_write_b32 v3, v32 offset:6336
	ds_write_b32 v3, v33 offset:6340
	ds_write_b32 v3, v34 offset:6344
	ds_write_b32 v3, v35 offset:6348
	ds_write_b32 v3, v36 offset:7392
	ds_write_b32 v3, v37 offset:7396
	ds_write_b32 v3, v38 offset:7400
	ds_write_b32 v3, v39 offset:7404
	s_addk_i32 s24, 0x800
	s_cmpk_ge_i32 s24, 0x3300
	s_cbranch_scc1 .Lcv_nonext
	s_mov_b32 s42, 1.0
	s_cmpk_ge_i32 s24, 0x1600
	s_cbranch_scc1 .Lcv_notup2
	s_cmpk_ge_i32 s24, 0xb00
	s_cselect_b32 s26, 1, 0
	s_mulk_i32 s26, 0xb00
	s_sub_i32 s25, s24, s26
	s_cmp_lg_u32 s26, 0
	s_cselect_b32 s43, 0xa0, 0x28
	s_mov_b32 s52, 0x800000
	s_cselect_b32 s52, 0x2980000, s52
	s_mul_i32 s27, s25, 0xba2f
	s_lshr_b32 s27, s27, 23
	s_mul_i32 s0, s27, 176
	s_sub_i32 s28, s25, s0
	s_lshl_b32 s28, s28, 5
	s_cmpk_ge_i32 s28, 0xb00
	s_cselect_b32 s0, 0xb00, 0
	s_cselect_b32 s1, 128, 0
	s_sub_i32 s0, s28, s0
	s_lshr_b32 s29, s0, 7
	s_lshl_b32 s29, s29, 8
	s_and_b32 s0, s0, 127
	s_add_i32 s29, s29, s0
	s_add_i32 s29, s29, s1
	s_mul_i32 s51, s19, 0x1600000
	s_movk_i32 s36, 0x5800
	s_movk_i32 s37, 0x800
	s_branch .Lcv_common2

; #define LAS __attribute__((address_space(3)))
; __device__ __forceinline__ unsigned pk2(float lo, float hi) { return pg8::cvt_pk_bf16(lo, hi); }
; #define LDS_WAIT() asm volatile("s_waitcnt lgkmcnt(0)" ::: "memory")
;     ...
;     LDS_WAIT();
;     const int c = lane & 7;
; #pragma unroll
;     for (int j = 0; j < 4; ++j) { const int n = (lane >> 3) + 8 * j; const LAS float* s = scr + (8 * c) * 33 + n;
;         u32x4 o; o.x = pk2(s[0 * 33] * sc, s[1 * 33] * sc); o.y = pk2(s[2 * 33] * sc, s[3 * 33] * sc); o.z = pk2(s[4 * 33] * sc, s[5 * 33] * sc); o.w = pk2(s[6 * 33] * sc, s[7 * 33] * sc);
;         *(u32x4*)(WT + (size_t)(outrow0 + n) * K + k0 + 8 * c) = o; }
;     LDS_WAIT();
.Lcv_nonext:
	v_mad_u32_u24 v6, v1, s53, v2
	s_lshl_b32 s0, s53, 3
	s_waitcnt lgkmcnt(0)
	ds_read_b32 v40, v4
	ds_read_b32 v41, v4 offset:132
	ds_read_b32 v42, v4 offset:264
	ds_read_b32 v43, v4 offset:396
	ds_read_b32 v44, v4 offset:528
	ds_read_b32 v45, v4 offset:660
	ds_read_b32 v46, v4 offset:792
	ds_read_b32 v47, v4 offset:924
	s_waitcnt lgkmcnt(0)
	v_mul_f32_e32 v40, s50, v40
	v_mul_f32_e32 v41, s50, v41
	v_mul_f32_e32 v42, s50, v42
	v_mul_f32_e32 v43, s50, v43
	v_mul_f32_e32 v44, s50, v44
	v_mul_f32_e32 v45, s50, v45
	v_mul_f32_e32 v46, s50, v46
	v_mul_f32_e32 v47, s50, v47
	v_cvt_pk_bf16_f32 v48, v40, v41
	v_cvt_pk_bf16_f32 v49, v42, v43
	v_cvt_pk_bf16_f32 v50, v44, v45
	v_cvt_pk_bf16_f32 v51, v46, v47
	global_store_dwordx4 v6, v[48:51], s[56:57]
	v_add_u32_e32 v6, s0, v6
	ds_read_b32 v40, v4 offset:32
	ds_read_b32 v41, v4 offset:164
	ds_read_b32 v42, v4 offset:296
	ds_read_b32 v43, v4 offset:428
	ds_read_b32 v44, v4 offset:560
	ds_read_b32 v45, v4 offset:692
	ds_read_b32 v46, v4 offset:824
	ds_read_b32 v47, v4 offset:956
	s_waitcnt lgkmcnt(0)
	v_mul_f32_e32 v40, s50, v40
	v_mul_f32_e32 v41, s50, v41
	v_mul_f32_e32 v42, s50, v42
	v_mul_f32_e32 v43, s50, v43
	v_mul_f32_e32 v44, s50, v44
	v_mul_f32_e32 v45, s50, v45
	v_mul_f32_e32 v46, s50, v46
	v_mul_f32_e32 v47, s50, v47
	v_cvt_pk_bf16_f32 v48, v40, v41
	v_cvt_pk_bf16_f32 v49, v42, v43
	v_cvt_pk_bf16_f32 v50, v44, v45
	v_cvt_pk_bf16_f32 v51, v46, v47
	global_store_dwordx4 v6, v[48:51], s[56:57]
	v_add_u32_e32 v6, s0, v6
	ds_read_b32 v40, v4 offset:64
	ds_read_b32 v41, v4 offset:196
	ds_read_b32 v42, v4 offset:328
	ds_read_b32 v43, v4 offset:460
	ds_read_b32 v44, v4 offset:592
	ds_read_b32 v45, v4 offset:724
	ds_read_b32 v46, v4 offset:856
	ds_read_b32 v47, v4 offset:988
	s_waitcnt lgkmcnt(0)
	v_mul_f32_e32 v40, s50, v40
	v_mul_f32_e32 v41, s50, v41
	v_mul_f32_e32 v42, s50, v42
	v_mul_f32_e32 v43, s50, v43
	v_mul_f32_e32 v44, s50, v44
	v_mul_f32_e32 v45, s50, v45
	v_mul_f32_e32 v46, s50, v46
	v_mul_f32_e32 v47, s50, v47
	v_cvt_pk_bf16_f32 v48, v40, v41
	v_cvt_pk_bf16_f32 v49, v42, v43
	v_cvt_pk_bf16_f32 v50, v44, v45
	v_cvt_pk_bf16_f32 v51, v46, v47
	global_store_dwordx4 v6, v[48:51], s[56:57]
	v_add_u32_e32 v6, s0, v6
	ds_read_b32 v40, v4 offset:96
	ds_read_b32 v41, v4 offset:228
	ds_read_b32 v42, v4 offset:360
	ds_read_b32 v43, v4 offset:492
	ds_read_b32 v44, v4 offset:624
	ds_read_b32 v45, v4 offset:756
	ds_read_b32 v46, v4 offset:888
	ds_read_b32 v47, v4 offset:1020
	s_waitcnt lgkmcnt(0)
	v_mul_f32_e32 v40, s50, v40
	v_mul_f32_e32 v41, s50, v41
	v_mul_f32_e32 v42, s50, v42
	v_mul_f32_e32 v43, s50, v43
	v_mul_f32_e32 v44, s50, v44
	v_mul_f32_e32 v45, s50, v45
	v_mul_f32_e32 v46, s50, v46
	v_mul_f32_e32 v47, s50, v47
	v_cvt_pk_bf16_f32 v48, v40, v41
	v_cvt_pk_bf16_f32 v49, v42, v43
	v_cvt_pk_bf16_f32 v50, v44, v45
	v_cvt_pk_bf16_f32 v51, v46, v47
	global_store_dwordx4 v6, v[48:51], s[56:57]
	s_cmpk_lt_i32 s24, 0x3300
	s_cbranch_scc0 .Lcv_done
	s_waitcnt vmcnt(4)
	s_branch .Lcv_loop
